# stack + MoBA partial outputs stored with plain (cache-allocating) stores for the combine phase that reads them next
# baseline (speedup 1.0000x reference)
.LBB0_404:
	ds_bpermute_b32 v32, v238, v162
	v_add_u32_e32 v241, 0x100, v241
	v_add_u32_e32 v240, 0x100, v240
	s_waitcnt lgkmcnt(0)
	v_add_f32_e32 v33, v162, v32
	v_div_scale_f32 v34, s[0:1], v33, v33, 1.0
	v_rcp_f32_e32 v35, v34
	v_div_scale_f32 v36, vcc, 1.0, v33, 1.0
	v_lshrrev_b32_e32 v32, 13, v195
	v_fma_f32 v37, -v34, v35, 1.0
	v_fmac_f32_e32 v35, v37, v35
	v_mul_f32_e32 v37, v36, v35
	v_fma_f32 v38, -v34, v37, v36
	v_fmac_f32_e32 v37, v38, v35
	v_fma_f32 v34, -v34, v37, v36
	v_div_fmas_f32 v34, v34, v35, v37
	v_div_fixup_f32 v34, v34, v33, 1.0
	v_mul_f32_e32 v34, 0x41800000, v34
	v_mul_f32_e32 v0, v0, v34
	v_mul_f32_e32 v1, v1, v34
	v_mul_f32_e32 v16, v16, v34
	v_mul_f32_e32 v17, v17, v34
	v_mul_f32_e32 v2, v2, v34
	v_mul_f32_e32 v18, v18, v34
	v_mul_f32_e32 v3, v3, v34
	v_mul_f32_e32 v19, v19, v34
	v_mul_f32_e32 v4, v4, v34
	v_mul_f32_e32 v20, v20, v34
	v_mul_f32_e32 v5, v5, v34
	v_mul_f32_e32 v21, v21, v34
	v_mul_f32_e32 v6, v6, v34
	v_mul_f32_e32 v22, v22, v34
	v_mul_f32_e32 v7, v7, v34
	v_mul_f32_e32 v23, v23, v34
	v_mul_f32_e32 v8, v8, v34
	v_mul_f32_e32 v24, v24, v34
	v_mul_f32_e32 v9, v9, v34
	v_mul_f32_e32 v25, v25, v34
	v_mul_f32_e32 v10, v10, v34
	v_mul_f32_e32 v26, v26, v34
	v_mul_f32_e32 v11, v11, v34
	v_mul_f32_e32 v27, v27, v34
	v_mul_f32_e32 v12, v12, v34
	v_mul_f32_e32 v28, v28, v34
	v_mul_f32_e32 v13, v13, v34
	v_mul_f32_e32 v29, v29, v34
	v_mul_f32_e32 v14, v14, v34
	v_mul_f32_e32 v30, v30, v34
	v_mul_f32_e32 v15, v15, v34
	v_mul_f32_e32 v31, v31, v34
	v_cvt_pk_fp8_f32 v36, v0, v1
	v_cvt_pk_fp8_f32 v36, v2, v3 op_sel:[0,0,1]
	v_cvt_pk_fp8_f32 v37, v4, v5
	v_cvt_pk_fp8_f32 v37, v6, v7 op_sel:[0,0,1]
	v_cvt_pk_fp8_f32 v38, v8, v9
	v_cvt_pk_fp8_f32 v38, v10, v11 op_sel:[0,0,1]
	v_cvt_pk_fp8_f32 v39, v12, v13
	v_cvt_pk_fp8_f32 v39, v14, v15 op_sel:[0,0,1]
	v_cvt_pk_fp8_f32 v40, v16, v17
	v_cvt_pk_fp8_f32 v40, v18, v19 op_sel:[0,0,1]
	v_cvt_pk_fp8_f32 v41, v20, v21
	v_cvt_pk_fp8_f32 v41, v22, v23 op_sel:[0,0,1]
	ds_write2_b32 v231, v36, v37 offset1:2
	ds_write2_b32 v231, v38, v39 offset0:4 offset1:6
	ds_write2_b32 v231, v40, v41 offset0:8 offset1:10
	v_cvt_pk_fp8_f32 v42, v24, v25
	v_cvt_pk_fp8_f32 v42, v26, v27 op_sel:[0,0,1]
	v_cvt_pk_fp8_f32 v43, v28, v29
	v_cvt_pk_fp8_f32 v43, v30, v31 op_sel:[0,0,1]
	v_lshlrev_b32_e32 v0, 13, v196
	v_cndmask_b32_e64 v1, 0, v236, s[80:81]
	v_or3_b32 v0, v0, v1, v194
	ds_bpermute_b32 v13, v239, v0
	ds_write2_b32 v231, v42, v43 offset0:12 offset1:14
	s_waitcnt lgkmcnt(0)
	v_mov_b32_e32 v14, s19
	v_log_f32_e32 v33, v33
	s_waitcnt lgkmcnt(1)
	v_lshrrev_b32_e32 v8, 13, v13
	v_and_b32_e32 v11, 3, v8
	v_lshlrev_b32_e32 v162, 25, v11
	v_and_b32_e32 v10, 0x1fff, v13
	v_lshl_add_u64 v[8:9], s[28:29], 0, v[162:163]
	v_cmp_eq_u32_e32 vcc, 3, v11
	v_mov_b32_e32 v11, s18
	v_or_b32_e32 v10, s10, v10
	v_cndmask_b32_e32 v8, v8, v11, vcc
	v_mov_b32_e32 v11, s11
	ds_read_b128 v[0:3], v237
	ds_read_b128 v[4:7], v237 offset:16
	v_cndmask_b32_e32 v9, v9, v14, vcc
	v_lshlrev_b64 v[10:11], 10, v[10:11]
	v_lshl_add_u64 v[8:9], v[8:9], 0, v[10:11]
	v_lshl_add_u64 v[8:9], v[8:9], 0, s[72:73]
	v_and_b32_e32 v10, 0x8000, v13
	v_lshl_add_u64 v[8:9], v[8:9], 0, v[172:173]
	v_cmp_eq_u32_e32 vcc, 0, v10
	v_add_f32_e32 v12, v197, v33
	v_mov_b32_e32 v197, v163
	v_cndmask_b32_e32 v9, v9, v175, vcc
	v_cndmask_b32_e32 v8, v8, v174, vcc
	s_waitcnt lgkmcnt(1)
	global_store_dwordx4 v[8:9], v[0:3], off
	s_waitcnt lgkmcnt(0)
	global_store_dwordx4 v[8:9], v[4:7], off offset:16
	v_ashrrev_i32_e32 v195, 31, v194
	v_lshlrev_b64 v[0:1], 15, v[196:197]
	v_lshl_add_u64 v[0:1], v[0:1], 0, s[10:11]
	v_lshl_add_u64 v[0:1], v[0:1], 0, v[194:195]
	v_lshlrev_b64 v[0:1], 6, v[0:1]
	v_lshl_add_u64 v[0:1], s[76:77], 0, v[0:1]
	v_cndmask_b32_e64 v1, v177, v1, s[80:81]
	v_cndmask_b32_e64 v0, v176, v0, s[80:81]
	s_and_b64 vcc, exec, s[84:85]
	global_store_dword v[0:1], v12, off
	s_cbranch_vccnz .LBB0_407
	s_waitcnt vmcnt(6)
	v_mov_b64_e32 v[108:109], v[124:125]
	s_waitcnt vmcnt(5)
	v_mov_b64_e32 v[104:105], v[120:121]
	s_waitcnt vmcnt(4)
	v_mov_b64_e32 v[100:101], v[116:117]
	s_waitcnt vmcnt(3)
	v_mov_b64_e32 v[96:97], v[112:113]
	s_mov_b64 s[80:81], s[82:83]
	v_mov_b64_e32 v[110:111], v[126:127]
	v_mov_b64_e32 v[106:107], v[122:123]
	v_mov_b64_e32 v[102:103], v[118:119]
	v_mov_b64_e32 v[98:99], v[114:115]
	v_mov_b32_e32 v196, v32
	v_mov_b32_e32 v194, v242
	s_mov_b32 s58, s8
	v_mov_b32_e32 v195, v243
	s_mov_b64 s[82:83], s[86:87]
	s_branch .LBB0_387
